# v23 + proj->out and out->up grid barriers split-phase with the w_up / w_dn weight transposes in their windows; w_pa, w_pb, w_out transposes moved from phase 0 into the in-proj->mixer barrier windows o
# baseline (speedup 1.0000x reference)
; __device__ __forceinline__ void prep_x(const int wv, const float* __restrict__ x, bf16_t* __restrict__ orbuf) {
;     const int wave = TIDX >> 6, lane = TIDX & 63;
;     const int rstride = gridDim.x * 8;
;     for (int row0 = blockIdx.x * 8 + wave; row0 < MT; row0 += 4 * rstride) {
;         f32x4 v[4][4];
; #pragma unroll
;         for (int q = 0; q < 4; ++q) { const int row = row0 + q * rstride;
;             if (row < MT) {
; #pragma unroll
;                 for (int i = 0; i < 4; ++i) v[q][i] = *(const f32x4*)(x + (size_t)row * DM + i * 256 + lane * 4);
;             } }
; __global__ void __launch_bounds__(512, 2) mega(Params p_unused) {
;     ...
;         transpose_w(wv, lds, kp->w_in, WSP(bf16_t, WS_WIN), DM, INW, kp->norm1_g, C_RK, C_RK + 1024, 0.0625f);
;         transpose_w(wv, lds, kp->w_pa, WSP(bf16_t, WS_WPA), 512, DM, nullptr, 0, 0, 1.f);
;         transpose_w(wv, lds, kp->w_pb, WSP(bf16_t, WS_WPB), 2048, DM, nullptr, 0, 0, 1.f);
;         transpose_w(wv, lds, kp->w_out, WSP(bf16_t, WS_WOUT), DM, DM, nullptr, 0, 0, 1.f);
;         transpose_w(wv, lds, kp->w_up, WSP(bf16_t, WS_WUP), DM, DFF, kp->norm2_g, 0, 0, 1.f);
;         transpose_w(wv, lds, kp->w_dn, WSP(bf16_t, WS_WDN), DFF, DM, nullptr, 0, 0, 1.f);
;         prep_x(wv, kp->x, WSP(bf16_t, WS_OR));
.LBB0_24:
.LBB0_27:
	s_cmpk_lt_i32 s66, 0x200
	s_cselect_b64 s[0:1], -1, 0
	s_cmpk_gt_i32 s66, 0x1ff
	v_writelane_b32 v253, s0, 0
	v_mbcnt_lo_u32_b32 v2, -1, 0
	v_mbcnt_hi_u32_b32 v2, -1, v2
	s_nop 1
	v_writelane_b32 v253, s1, 1
.LBB0_30:
.LBB0_33:
.LBB0_55:
	v_mbcnt_lo_u32_b32 v2, -1, 0
	v_mbcnt_hi_u32_b32 v2, -1, v2
	s_mov_b32 s14, 0x8000
	v_add_u32_e32 v2, s53, v2
	v_ashrrev_i32_e32 v3, 6, v2
	v_lshl_add_u32 v78, s66, 3, v3
	v_cmp_gt_i32_e32 vcc, s14, v78
	v_mbcnt_lo_u32_b32 v2, -1, 0
	v_mbcnt_hi_u32_b32 v2, -1, v2
	s_and_saveexec_b64 s[6:7], vcc
	s_cbranch_execz .LBB0_70
	s_load_dwordx2 s[0:1], s[2:3], 0x0
	v_lshlrev_b32_e32 v2, 2, v2
	s_waitcnt lgkmcnt(0)
	s_add_u32 s10, s10, 0x15400000
	v_and_b32_e32 v66, 0xfc, v2
	s_addc_u32 s11, s11, 0
	s_lshl_b32 s15, s54, 3
	v_mov_b32_e32 v69, 0
	v_lshlrev_b32_e32 v68, 2, v66
	v_lshl_add_u64 v[70:71], s[0:1], 0, v[68:69]
	v_bfrev_b32_e32 v3, 0.5
	s_movk_i32 s0, 0x80
	s_add_i32 s19, s15, s15
	v_bitop3_b32 v67, v2, 4, v3 bitop3:0x6c
	v_bitop3_b32 v80, v2, 8, v3 bitop3:0x6c
	v_bitop3_b32 v81, v2, 16, v3 bitop3:0x6c
	v_bitop3_b32 v82, v2, 32, v3 bitop3:0x6c
	v_bitop3_b32 v83, v2, 64, v3 bitop3:0x6c
	v_bitop3_b32 v84, v2, s0, v3 bitop3:0x6c
	s_lshl_b32 s16, s54, 4
	s_mul_i32 s17, s54, 24
	s_mov_b64 s[12:13], 0
	v_mov_b32_e32 v85, 0x358637bd
	s_mov_b32 s18, 0x800000
	s_add_i32 s19, s19, s15
	s_movk_i32 s20, 0x3fff
	s_branch .LBB0_58

; #define LAS __attribute__((address_space(3)))
; __device__ __forceinline__ unsigned cvt_pk_bf16(float lo, float hi) { unsigned r; asm volatile("v_cvt_pk_bf16_f32 %0, %1, %2" : "=v"(r) : "v"(lo), "v"(hi)); return r; }
; __device__ __forceinline__ void transpose_w(const int wv, LAS unsigned char* lds, const float* __restrict__ w, bf16_t* __restrict__ wt, int K, int N, const float* __restrict__ gk, int slo, int shi, float scale) {
;     const int tk = K / 64, tn = N / 64, nt = tk * tn;
;     const int t = TIDX, nl = t & 63, kg = t >> 6, n2 = t >> 3, kc = t & 7;
;     for (int tile = blockIdx.x; tile < nt; tile += gridDim.x) {
;         const int kt0 = (tile % tk) * 64, nb0 = (tile / tk) * 64;
;         const int k0 = kt0 + kg * 8, n = nb0 + nl;
;         float v[8];
; #pragma unroll
;         for (int j = 0; j < 8; ++j) { float g = gk ? gk[k0 + j] : 1.0f; v[j] = w[(size_t)(k0 + j) * N + n] * g; }
;         if (n >= slo && n < shi) {
; #pragma unroll
;             for (int j = 0; j < 8; ++j) v[j] *= scale;
;         }
;         u32x4 o; o.x = cvt_pk_bf16(v[0], v[1]); o.y = cvt_pk_bf16(v[2], v[3]); o.z = cvt_pk_bf16(v[4], v[5]); o.w = cvt_pk_bf16(v[6], v[7]);
;         *(LAS u32x4*)(lds + nl * 144 + kg * 16) = o;
;         __syncthreads();
;         *(u32x4*)(wt + (size_t)(nb0 + n2) * K + kt0 + kc * 8) = *(const LAS u32x4*)(lds + n2 * 144 + kc * 16);
;         __syncthreads();
;     }
; }
.Lwin_t:
	s_mov_b64 s[2:3], s[56:57]
	s_load_dwordx2 s[10:11], s[56:57], 0x70
	s_waitcnt lgkmcnt(0)
	s_cmp_eq_u32 s79, 2
	s_cbranch_scc0 .Lwin_dn
	v_mbcnt_lo_u32_b32 v2, -1, 0
	v_mbcnt_hi_u32_b32 v2, -1, v2
	s_load_dwordx2 s[0:1], s[2:3], 0x40
	v_add_u32_e32 v3, s53, v2
	v_ashrrev_i32_e32 v5, 3, v3
	v_ashrrev_i32_e32 v3, 6, v3
	s_movk_i32 s6, 0x90
	v_and_b32_e32 v4, 63, v2
	v_and_b32_e32 v2, 7, v2
	v_lshlrev_b32_e32 v6, 3, v3
	v_lshlrev_b32_e32 v8, 4, v3
	v_mul_lo_u32 v3, v5, s6
	s_waitcnt lgkmcnt(0)
	s_add_u32 s4, s10, 0x1a00000
	v_mad_u32_u24 v7, v4, s6, 0
	v_add_u32_e32 v9, 0, v3
	v_lshlrev_b32_e32 v10, 4, v2
	v_lshlrev_b32_e32 v2, 3, v2
	s_addc_u32 s5, s11, 0
	v_mov_b32_e32 v3, 0
	s_lshl_b32 s12, s66, 6
	s_lshl_b32 s13, s54, 6
	v_add_u32_e32 v7, v7, v8
	v_add_u32_e32 v8, v9, v10
	v_lshlrev_b32_e32 v2, 1, v2
	s_mov_b32 s14, s66
.Lwb_29:
	s_ashr_i32 s6, s14, 31
	s_lshr_b32 s6, s6, 27
	s_add_i32 s6, s14, s6
	s_ashr_i32 s6, s6, 5
	s_lshl_b32 s7, s6, 11
	s_lshl_b32 s15, s6, 6
	s_sub_i32 s6, s12, s7
	v_or_b32_e32 v10, s15, v4
	v_add_u32_e32 v12, s6, v6
	v_ashrrev_i32_e32 v11, 31, v10
	v_ashrrev_i32_e32 v13, 31, v12
	v_add_u32_e32 v14, 1, v12
	v_add_u32_e32 v16, 2, v12
	v_add_u32_e32 v18, 3, v12
	v_add_u32_e32 v20, 4, v12
	v_add_u32_e32 v22, 5, v12
	v_add_u32_e32 v24, 6, v12
	v_add_u32_e32 v26, 7, v12
	v_lshl_add_u64 v[10:11], v[10:11], 2, s[0:1]
	v_lshlrev_b64 v[12:13], 12, v[12:13]
	v_ashrrev_i32_e32 v15, 31, v14
	v_ashrrev_i32_e32 v17, 31, v16
	v_ashrrev_i32_e32 v19, 31, v18
	v_ashrrev_i32_e32 v21, 31, v20
	v_ashrrev_i32_e32 v23, 31, v22
	v_ashrrev_i32_e32 v25, 31, v24
	v_ashrrev_i32_e32 v27, 31, v26
	v_lshl_add_u64 v[12:13], v[10:11], 0, v[12:13]
	v_lshlrev_b64 v[14:15], 12, v[14:15]
	v_lshlrev_b64 v[16:17], 12, v[16:17]
	v_lshlrev_b64 v[18:19], 12, v[18:19]
	v_lshlrev_b64 v[20:21], 12, v[20:21]
	v_lshlrev_b64 v[22:23], 12, v[22:23]
	v_lshlrev_b64 v[24:25], 12, v[24:25]
	v_lshlrev_b64 v[26:27], 12, v[26:27]
	v_lshl_add_u64 v[14:15], v[10:11], 0, v[14:15]
	v_lshl_add_u64 v[16:17], v[10:11], 0, v[16:17]
	v_lshl_add_u64 v[18:19], v[10:11], 0, v[18:19]
	v_lshl_add_u64 v[20:21], v[10:11], 0, v[20:21]
	v_lshl_add_u64 v[22:23], v[10:11], 0, v[22:23]
	v_lshl_add_u64 v[24:25], v[10:11], 0, v[24:25]
	v_lshl_add_u64 v[10:11], v[10:11], 0, v[26:27]
	global_load_dword v9, v[12:13], off nt
	global_load_dword v26, v[14:15], off nt
	global_load_dword v27, v[18:19], off nt
	global_load_dword v28, v[24:25], off nt
	global_load_dword v29, v[20:21], off nt
	global_load_dword v30, v[16:17], off nt
	global_load_dword v31, v[22:23], off nt
	global_load_dword v32, v[10:11], off nt
	v_add_u32_e32 v10, s15, v5
	v_ashrrev_i32_e32 v11, 31, v10
	v_lshlrev_b64 v[10:11], 12, v[10:11]
	s_ashr_i32 s7, s6, 31
	v_lshl_add_u64 v[10:11], s[4:5], 0, v[10:11]
	v_lshl_add_u64 v[14:15], s[6:7], 1, v[10:11]
	s_add_i32 s14, s14, s54
	s_add_i32 s12, s12, s13
	s_cmpk_lt_i32 s14, 0x200
	v_lshl_add_u64 v[14:15], v[14:15], 0, v[2:3]
	s_waitcnt vmcnt(6)
	v_cvt_pk_bf16_f32 v10, v9, v26
	s_waitcnt vmcnt(2)
	v_cvt_pk_bf16_f32 v11, v30, v27
	s_waitcnt vmcnt(1)
	v_cvt_pk_bf16_f32 v12, v29, v31
	s_waitcnt vmcnt(0)
	v_cvt_pk_bf16_f32 v13, v28, v32
	ds_write_b128 v7, v[10:13]
	s_waitcnt lgkmcnt(0)
	s_barrier
	ds_read_b128 v[10:13], v8
	s_waitcnt lgkmcnt(0)
	global_store_dwordx4 v[14:15], v[10:13], off
	s_barrier
	s_cbranch_scc1 .Lwb_29
	s_branch .Lwin_wait

; #define LAS __attribute__((address_space(3)))
; __device__ __forceinline__ unsigned cvt_pk_bf16(float lo, float hi) { unsigned r; asm volatile("v_cvt_pk_bf16_f32 %0, %1, %2" : "=v"(r) : "v"(lo), "v"(hi)); return r; }
; __device__ __forceinline__ void transpose_w(const int wv, LAS unsigned char* lds, const float* __restrict__ w, bf16_t* __restrict__ wt, int K, int N, const float* __restrict__ gk, int slo, int shi, float scale) {
;     const int tk = K / 64, tn = N / 64, nt = tk * tn;
;     const int t = TIDX, nl = t & 63, kg = t >> 6, n2 = t >> 3, kc = t & 7;
;     for (int tile = blockIdx.x; tile < nt; tile += gridDim.x) {
;         const int kt0 = (tile % tk) * 64, nb0 = (tile / tk) * 64;
;         const int k0 = kt0 + kg * 8, n = nb0 + nl;
;         float v[8];
; #pragma unroll
;         for (int j = 0; j < 8; ++j) { float g = gk ? gk[k0 + j] : 1.0f; v[j] = w[(size_t)(k0 + j) * N + n] * g; }
;         if (n >= slo && n < shi) {
; #pragma unroll
;             for (int j = 0; j < 8; ++j) v[j] *= scale;
;         }
;         u32x4 o; o.x = cvt_pk_bf16(v[0], v[1]); o.y = cvt_pk_bf16(v[2], v[3]); o.z = cvt_pk_bf16(v[4], v[5]); o.w = cvt_pk_bf16(v[6], v[7]);
;         *(LAS u32x4*)(lds + nl * 144 + kg * 16) = o;
;         __syncthreads();
;         *(u32x4*)(wt + (size_t)(nb0 + n2) * K + kt0 + kc * 8) = *(const LAS u32x4*)(lds + n2 * 144 + kc * 16);
;         __syncthreads();
;     }
; }
.Lwa_26:
	s_ashr_i32 s6, s14, 31
	s_lshr_b32 s6, s6, 29
	s_add_i32 s6, s14, s6
	s_ashr_i32 s6, s6, 3
	s_lshl_b32 s7, s6, 9
	s_lshl_b32 s15, s6, 6
	s_sub_i32 s6, s12, s7
	v_or_b32_e32 v10, s15, v4
	v_add_u32_e32 v12, s6, v6
	v_ashrrev_i32_e32 v11, 31, v10
	v_ashrrev_i32_e32 v13, 31, v12
	v_add_u32_e32 v14, 1, v12
	v_add_u32_e32 v16, 2, v12
	v_add_u32_e32 v18, 3, v12
	v_add_u32_e32 v20, 4, v12
	v_add_u32_e32 v22, 5, v12
	v_add_u32_e32 v24, 6, v12
	v_add_u32_e32 v26, 7, v12
	v_lshl_add_u64 v[10:11], v[10:11], 2, s[0:1]
	v_lshlrev_b64 v[12:13], 12, v[12:13]
	v_ashrrev_i32_e32 v15, 31, v14
	v_ashrrev_i32_e32 v17, 31, v16
	v_ashrrev_i32_e32 v19, 31, v18
	v_ashrrev_i32_e32 v21, 31, v20
	v_ashrrev_i32_e32 v23, 31, v22
	v_ashrrev_i32_e32 v25, 31, v24
	v_ashrrev_i32_e32 v27, 31, v26
	v_lshl_add_u64 v[12:13], v[10:11], 0, v[12:13]
	v_lshlrev_b64 v[14:15], 12, v[14:15]
	v_lshlrev_b64 v[16:17], 12, v[16:17]
	v_lshlrev_b64 v[18:19], 12, v[18:19]
	v_lshlrev_b64 v[20:21], 12, v[20:21]
	v_lshlrev_b64 v[22:23], 12, v[22:23]
	v_lshlrev_b64 v[24:25], 12, v[24:25]
	v_lshlrev_b64 v[26:27], 12, v[26:27]
	v_lshl_add_u64 v[14:15], v[10:11], 0, v[14:15]
	v_lshl_add_u64 v[16:17], v[10:11], 0, v[16:17]
	v_lshl_add_u64 v[18:19], v[10:11], 0, v[18:19]
	v_lshl_add_u64 v[20:21], v[10:11], 0, v[20:21]
	v_lshl_add_u64 v[22:23], v[10:11], 0, v[22:23]
	v_lshl_add_u64 v[24:25], v[10:11], 0, v[24:25]
	v_lshl_add_u64 v[10:11], v[10:11], 0, v[26:27]
	global_load_dword v9, v[12:13], off nt
	global_load_dword v26, v[14:15], off nt
	global_load_dword v27, v[18:19], off nt
	global_load_dword v28, v[24:25], off nt
	global_load_dword v29, v[20:21], off nt
	global_load_dword v30, v[16:17], off nt
	global_load_dword v31, v[22:23], off nt
	global_load_dword v32, v[10:11], off nt
	v_add_u32_e32 v10, s15, v5
	v_ashrrev_i32_e32 v11, 31, v10
	v_lshlrev_b64 v[10:11], 10, v[10:11]
	s_ashr_i32 s7, s6, 31
	v_lshl_add_u64 v[10:11], s[4:5], 0, v[10:11]
	v_lshl_add_u64 v[14:15], s[6:7], 1, v[10:11]
	s_add_i32 s14, s14, s54
	s_add_i32 s12, s12, s13
	s_cmpk_lt_i32 s14, 0x80
	v_lshl_add_u64 v[14:15], v[14:15], 0, v[2:3]
	s_waitcnt vmcnt(6)
	v_cvt_pk_bf16_f32 v10, v9, v26
	s_waitcnt vmcnt(2)
	v_cvt_pk_bf16_f32 v11, v30, v27
	s_waitcnt vmcnt(1)
	v_cvt_pk_bf16_f32 v12, v29, v31
	s_waitcnt vmcnt(0)
	v_cvt_pk_bf16_f32 v13, v28, v32
	ds_write_b128 v7, v[10:13]
	s_waitcnt lgkmcnt(0)
	s_barrier
	ds_read_b128 v[10:13], v8
	s_waitcnt lgkmcnt(0)
	global_store_dwordx4 v[14:15], v[10:13], off
	s_barrier
	s_cbranch_scc1 .Lwa_26
.Lwa_end:
	s_cmpk_gt_i32 s66, 0xff
	v_mbcnt_lo_u32_b32 v2, -1, 0
	v_mbcnt_hi_u32_b32 v2, -1, v2
	s_cbranch_scc1 .Lwin_wait
	s_load_dwordx2 s[0:1], s[2:3], 0x48
	v_add_u32_e32 v3, s53, v2
	v_ashrrev_i32_e32 v5, 3, v3
	v_ashrrev_i32_e32 v3, 6, v3
	s_movk_i32 s6, 0x90
	v_and_b32_e32 v4, 63, v2
	v_and_b32_e32 v2, 7, v2
	v_lshlrev_b32_e32 v6, 3, v3
	v_lshlrev_b32_e32 v8, 4, v3
	v_mul_lo_u32 v3, v5, s6
	s_waitcnt lgkmcnt(0)
	s_add_u32 s4, s10, 0x1e00000
	v_mad_u32_u24 v7, v4, s6, 0
	v_add_u32_e32 v9, 0, v3
	v_lshlrev_b32_e32 v10, 4, v2
	v_lshlrev_b32_e32 v2, 3, v2
	s_addc_u32 s5, s11, 0
	v_mov_b32_e32 v3, 0
	s_lshl_b32 s12, s66, 6
	s_lshl_b32 s13, s54, 6
	v_add_u32_e32 v7, v7, v8
	v_add_u32_e32 v8, v9, v10
	v_lshlrev_b32_e32 v2, 1, v2
	s_mov_b32 s14, s66
.Lwo_32:
	s_ashr_i32 s6, s14, 31
	s_lshr_b32 s6, s6, 28
	s_add_i32 s6, s14, s6
	s_ashr_i32 s6, s6, 4
	s_lshl_b32 s7, s6, 10
	s_lshl_b32 s15, s6, 6
	s_sub_i32 s6, s12, s7
	v_or_b32_e32 v10, s15, v4
	v_add_u32_e32 v12, s6, v6
	v_ashrrev_i32_e32 v11, 31, v10
	v_ashrrev_i32_e32 v13, 31, v12
	v_add_u32_e32 v14, 1, v12
	v_add_u32_e32 v16, 2, v12
	v_add_u32_e32 v18, 3, v12
	v_add_u32_e32 v20, 4, v12
	v_add_u32_e32 v22, 5, v12
	v_add_u32_e32 v24, 6, v12
	v_add_u32_e32 v26, 7, v12
	v_lshl_add_u64 v[10:11], v[10:11], 2, s[0:1]
	v_lshlrev_b64 v[12:13], 12, v[12:13]
	v_ashrrev_i32_e32 v15, 31, v14
	v_ashrrev_i32_e32 v17, 31, v16
	v_ashrrev_i32_e32 v19, 31, v18
	v_ashrrev_i32_e32 v21, 31, v20
	v_ashrrev_i32_e32 v23, 31, v22
	v_ashrrev_i32_e32 v25, 31, v24
	v_ashrrev_i32_e32 v27, 31, v26
	v_lshl_add_u64 v[12:13], v[10:11], 0, v[12:13]
	v_lshlrev_b64 v[14:15], 12, v[14:15]
	v_lshlrev_b64 v[16:17], 12, v[16:17]
	v_lshlrev_b64 v[18:19], 12, v[18:19]
	v_lshlrev_b64 v[20:21], 12, v[20:21]
	v_lshlrev_b64 v[22:23], 12, v[22:23]
	v_lshlrev_b64 v[24:25], 12, v[24:25]
	v_lshlrev_b64 v[26:27], 12, v[26:27]
	v_lshl_add_u64 v[14:15], v[10:11], 0, v[14:15]
	v_lshl_add_u64 v[16:17], v[10:11], 0, v[16:17]
	v_lshl_add_u64 v[18:19], v[10:11], 0, v[18:19]
	v_lshl_add_u64 v[20:21], v[10:11], 0, v[20:21]
	v_lshl_add_u64 v[22:23], v[10:11], 0, v[22:23]
	v_lshl_add_u64 v[24:25], v[10:11], 0, v[24:25]
	v_lshl_add_u64 v[10:11], v[10:11], 0, v[26:27]
	global_load_dword v9, v[12:13], off nt
	global_load_dword v26, v[14:15], off nt
	global_load_dword v27, v[18:19], off nt
	global_load_dword v28, v[24:25], off nt
	global_load_dword v29, v[20:21], off nt
	global_load_dword v30, v[16:17], off nt
	global_load_dword v31, v[22:23], off nt
	global_load_dword v32, v[10:11], off nt
	v_add_u32_e32 v10, s15, v5
	v_ashrrev_i32_e32 v11, 31, v10
	v_lshlrev_b64 v[10:11], 11, v[10:11]
	s_ashr_i32 s7, s6, 31
	v_lshl_add_u64 v[10:11], s[4:5], 0, v[10:11]
	v_lshl_add_u64 v[14:15], s[6:7], 1, v[10:11]
	s_add_i32 s14, s14, s54
	s_add_i32 s12, s12, s13
	s_cmpk_lt_i32 s14, 0x100
	v_lshl_add_u64 v[14:15], v[14:15], 0, v[2:3]
	s_waitcnt vmcnt(6)
	v_cvt_pk_bf16_f32 v10, v9, v26
	s_waitcnt vmcnt(2)
	v_cvt_pk_bf16_f32 v11, v30, v27
	s_waitcnt vmcnt(1)
	v_cvt_pk_bf16_f32 v12, v29, v31
	s_waitcnt vmcnt(0)
	v_cvt_pk_bf16_f32 v13, v28, v32
	ds_write_b128 v7, v[10:13]
	s_waitcnt lgkmcnt(0)
	s_barrier
	ds_read_b128 v[10:13], v8
	s_waitcnt lgkmcnt(0)
	global_store_dwordx4 v[14:15], v[10:13], off
	s_barrier
	s_cbranch_scc1 .Lwo_32
.Lwin_wait:
	s_cmp_eq_u32 s101, 0
	s_cbranch_scc1 .Lgwb1_done
	v_mov_b32_e32 v222, s98
	v_mov_b32_e32 v223, s99

; __device__ __forceinline__ unsigned xb_ld(unsigned* p)              { return __hip_atomic_load(p, __ATOMIC_RELAXED, __HIP_MEMORY_SCOPE_AGENT); }
; __device__ __forceinline__ unsigned xb_add(unsigned* p, unsigned v) { return __hip_atomic_fetch_add(p, v, __ATOMIC_RELAXED, __HIP_MEMORY_SCOPE_AGENT); }
; #define XB_SPIN(cond, bar) do { unsigned _sp = 0; while (cond) { __builtin_amdgcn_s_sleep(1); \
;     if ((++_sp & 255u) == 0u) { if (xb_ld(&(bar)[XB_TMO])) break; if (_sp > XB_SPIN_CAP) { atomicAdd(&(bar)[XB_TMO], 1u); break; } } } } while (0)
; __device__ __forceinline__ void xcd_barrier(const int wv, const XcdBarrier& b) {
;     ...
;         const unsigned old = xb_add(&bar[XB_XSUB(b.x)], 1u);
;         const unsigned gen = old / nloc;
;         if (old + 1u == (gen + 1u) * nloc) {
;             __builtin_amdgcn_fence(__ATOMIC_RELEASE, "agent");
;             asm volatile("s_waitcnt vmcnt(0)" ::: "memory");
;             const unsigned og = xb_add(&bar[XB_TOP], 1u);
;             const unsigned tg = og / nx;
;             if (og + 1u == (tg + 1u) * nx) xb_add(&bar[XB_TOPGEN], 1u);
;             else XB_SPIN(xb_ld(&bar[XB_TOPGEN]) == tg, bar);
;             __builtin_amdgcn_fence(__ATOMIC_ACQUIRE, "agent");
;             xb_add(&bar[XB_XGEN(b.x)], 1u);
;             asm volatile("s_waitcnt vmcnt(0)" ::: "memory");
;         } else {
;             XB_SPIN(xb_ld(&bar[XB_XGEN(b.x)]) == gen, bar);
.LBB0_617:
	v_lshl_add_u64 v[0:1], v[178:179], 2, s[2:3]
	v_add_co_u32_e32 v6, vcc, 0x1000, v0
	v_mov_b32_e32 v3, 1
	s_nop 0
	v_addc_co_u32_e32 v7, vcc, 0, v1, vcc
	flat_atomic_add v3, v[6:7], v3 offset:1024 sc0
	v_cvt_f32_u32_e32 v5, v4
	v_sub_u32_e32 v6, 0, v4
	v_rcp_iflag_f32_e32 v5, v5
	s_nop 0
	v_mul_f32_e32 v5, 0x4f7ffffe, v5
	v_cvt_u32_f32_e32 v5, v5
	v_mul_lo_u32 v6, v6, v5
	v_mul_hi_u32 v6, v5, v6
	v_add_u32_e32 v5, v5, v6
	s_waitcnt vmcnt(0) lgkmcnt(0)
	v_mul_hi_u32 v5, v3, v5
	v_mul_lo_u32 v7, v5, v4
	v_add_u32_e32 v6, 1, v3
	v_sub_u32_e32 v3, v3, v7
	v_add_u32_e32 v8, 1, v5
	v_cmp_ge_u32_e32 vcc, v3, v4
	v_sub_u32_e32 v7, v3, v4
	s_nop 0
	v_cndmask_b32_e32 v5, v5, v8, vcc
	v_cndmask_b32_e32 v3, v3, v7, vcc
	v_add_u32_e32 v7, 1, v5
	v_cmp_ge_u32_e32 vcc, v3, v4
	s_nop 1
	v_cndmask_b32_e32 v3, v5, v7, vcc
	v_mad_u64_u32 v[4:5], s[4:5], v4, v3, v[4:5]
	v_cmp_ne_u32_e32 vcc, v6, v4
	s_and_saveexec_b64 s[4:5], vcc
	s_xor_b64 s[4:5], exec, s[4:5]
	s_cbranch_execz .LBB0_630
	v_add_co_u32_e32 v4, vcc, 0x2400, v0
	s_nop 1
	v_addc_co_u32_e32 v5, vcc, 0, v1, vcc
	s_nop 0
	v_readfirstlane_b32 s98, v4
	v_readfirstlane_b32 s99, v5
	v_readfirstlane_b32 s100, v3
	s_mov_b32 s101, 0x40000

; #define LAS __attribute__((address_space(3)))
; __device__ __forceinline__ void transpose_w(const int wv, LAS unsigned char* lds, const float* __restrict__ w, bf16_t* __restrict__ wt, int K, int N, const float* __restrict__ gk, int slo, int shi, float scale) {
;     const int tk = K / 64, tn = N / 64, nt = tk * tn;
;     const int t = TIDX, nl = t & 63, kg = t >> 6, n2 = t >> 3, kc = t & 7;
;     for (int tile = blockIdx.x; tile < nt; tile += gridDim.x) {
;         const int kt0 = (tile % tk) * 64, nb0 = (tile / tk) * 64;
;         const int k0 = kt0 + kg * 8, n = nb0 + nl;
;         float v[8];
; #pragma unroll
;         for (int j = 0; j < 8; ++j) { float g = gk ? gk[k0 + j] : 1.0f; v[j] = w[(size_t)(k0 + j) * N + n] * g; }
.LBB0_646:
	s_or_b64 exec, exec, s[0:1]
	s_mov_b64 s[2:3], s[56:57]
	s_waitcnt lgkmcnt(0)
	s_barrier
	s_mov_b64 s[2:3], s[56:57]
	s_load_dwordx2 s[10:11], s[56:57], 0x70
	s_waitcnt lgkmcnt(0)
	s_cmpk_lt_i32 s66, 0x400
	s_cselect_b64 s[12:13], -1, 0
	s_cmpk_gt_i32 s66, 0x3ff
	v_mbcnt_lo_u32_b32 v2, -1, 0
	v_mbcnt_hi_u32_b32 v2, -1, v2
	s_cbranch_scc1 .Lw2_wait
	s_load_dwordx4 s[4:7], s[2:3], 0x50
	s_waitcnt lgkmcnt(0)
	s_add_u32 s14, s10, 0x2000000
	s_addc_u32 s15, s11, 0
	v_add_u32_e32 v3, s53, v2
	v_ashrrev_i32_e32 v11, 3, v3
	v_ashrrev_i32_e32 v3, 6, v3
	s_cmp_lg_u64 s[4:5], 0
	s_movk_i32 s16, 0x90
	v_and_b32_e32 v10, 63, v2
	v_and_b32_e32 v2, 7, v2
	v_lshlrev_b32_e32 v12, 3, v3
	s_cselect_b64 s[0:1], -1, 0
	v_lshlrev_b32_e32 v5, 4, v3
	v_mul_lo_u32 v3, v11, s16
	v_mad_u32_u24 v4, v10, s16, 0
	v_add_u32_e32 v6, 0, v3
	v_lshlrev_b32_e32 v7, 4, v2
	v_lshlrev_b32_e32 v2, 3, v2
	v_cndmask_b32_e64 v8, 0, 1, s[0:1]
	v_mov_b32_e32 v3, 0
	s_lshl_b32 s16, s66, 6
	s_lshl_b32 s17, s54, 6
	v_cmp_ne_u32_e64 s[0:1], 1, v8
	v_add_u32_e32 v13, v4, v5
	v_add_u32_e32 v14, v6, v7
	v_lshlrev_b32_e32 v2, 1, v2
	s_mov_b32 s18, s66
	s_branch .Lwu_36

; #define LAS __attribute__((address_space(3)))
; __device__ __forceinline__ unsigned cvt_pk_bf16(float lo, float hi) { unsigned r; asm volatile("v_cvt_pk_bf16_f32 %0, %1, %2" : "=v"(r) : "v"(lo), "v"(hi)); return r; }
; __device__ __forceinline__ void transpose_w(const int wv, LAS unsigned char* lds, const float* __restrict__ w, bf16_t* __restrict__ wt, int K, int N, const float* __restrict__ gk, int slo, int shi, float scale) {
;     const int tk = K / 64, tn = N / 64, nt = tk * tn;
;     const int t = TIDX, nl = t & 63, kg = t >> 6, n2 = t >> 3, kc = t & 7;
;     for (int tile = blockIdx.x; tile < nt; tile += gridDim.x) {
;         const int kt0 = (tile % tk) * 64, nb0 = (tile / tk) * 64;
;         const int k0 = kt0 + kg * 8, n = nb0 + nl;
;         float v[8];
; #pragma unroll
;         for (int j = 0; j < 8; ++j) { float g = gk ? gk[k0 + j] : 1.0f; v[j] = w[(size_t)(k0 + j) * N + n] * g; }
;         if (n >= slo && n < shi) {
; #pragma unroll
;             for (int j = 0; j < 8; ++j) v[j] *= scale;
;         }
;         u32x4 o; o.x = cvt_pk_bf16(v[0], v[1]); o.y = cvt_pk_bf16(v[2], v[3]); o.z = cvt_pk_bf16(v[4], v[5]); o.w = cvt_pk_bf16(v[6], v[7]);
;         *(LAS u32x4*)(lds + nl * 144 + kg * 16) = o;
;         __syncthreads();
;         *(u32x4*)(wt + (size_t)(nb0 + n2) * K + kt0 + kc * 8) = *(const LAS u32x4*)(lds + n2 * 144 + kc * 16);
;         __syncthreads();
;     }
; }
.Lwu_50:
	v_add_u32_e32 v28, 6, v4
	v_ashrrev_i32_e32 v29, 31, v28
	v_lshlrev_b64 v[28:29], 14, v[28:29]
	v_lshl_add_u64 v[28:29], v[6:7], 0, v[28:29]
	global_load_dword v28, v[28:29], off nt
	s_and_b64 vcc, exec, s[0:1]
	s_cbranch_vccnz .Lwu_35
	global_load_dword v21, v[8:9], off offset:28 nt
	s_branch .Lwu_35
.Lw2_wait:
	s_cmp_eq_u32 s101, 0
	s_cbranch_scc1 .Lgwt2_done
	v_mov_b32_e32 v222, s98
	v_mov_b32_e32 v223, s99

;     __device__ void init(int b_, int G_, int c_) { so.init(TB, 42 * 256, G_, c_); G = G_; c = c_; b = b_; gstart = b_ == 0 ? 0 : 256 + 192 * b_; ng = b_ == 0 ? 448 : 192; }
; __device__ __forceinline__ KParams kparams() { unsigned long long a = (unsigned long long)__builtin_amdgcn_kernarg_segment_ptr(); asm volatile("" : "+s"(a)); return (KParams)a; }
; __global__ void __launch_bounds__(512, 2) mega(Params p_unused) {
;     ...
;     {
;         KParams kp = kparams(); unsigned char* ws = kp->ws;
;         pg8::StaticOrder S; S.init(MT, DM, (int)gridDim.x, (int)blockIdx.x);
;         pg8::Gemm gm{WSP(bf16_t, WS_Y), WSP(bf16_t, WS_WOUT), MT, DM, DM, DM, DM}; EpiOut E{kp->x, WSP(bf16_t, WS_X1B), WSP(float, WS_SS2)};
;         pg8::gemm_phase<EpiOut, pg8::StaticOrder>(wv, lds, gm, S, E);
.Lgwt2_done:
	s_barrier
	s_mov_b64 s[2:3], s[56:57]
	s_cmpk_lt_u32 s53, 0x100
	s_cbranch_scc1 .Lgprio_out
	s_setprio 1

; #define LAS __attribute__((address_space(3)))
; __device__ __forceinline__ void transpose_w(const int wv, LAS unsigned char* lds, const float* __restrict__ w, bf16_t* __restrict__ wt, int K, int N, const float* __restrict__ gk, int slo, int shi, float scale) {
;     const int tk = K / 64, tn = N / 64, nt = tk * tn;
;     const int t = TIDX, nl = t & 63, kg = t >> 6, n2 = t >> 3, kc = t & 7;
;     for (int tile = blockIdx.x; tile < nt; tile += gridDim.x) {
;         const int kt0 = (tile % tk) * 64, nb0 = (tile / tk) * 64;
;         const int k0 = kt0 + kg * 8, n = nb0 + nl;
;         float v[8];
; #pragma unroll
;         for (int j = 0; j < 8; ++j) { float g = gk ? gk[k0 + j] : 1.0f; v[j] = w[(size_t)(k0 + j) * N + n] * g; }
.LBB0_710:
	s_or_b64 exec, exec, s[0:1]
	s_mov_b64 s[0:1], s[56:57]
	s_waitcnt lgkmcnt(0)
	s_barrier
	s_mov_b64 s[2:3], s[56:57]
	s_load_dwordx2 s[10:11], s[56:57], 0x70
	s_waitcnt lgkmcnt(0)
	s_mov_b64 s[12:13], -1
	s_andn2_b64 vcc, exec, s[12:13]
	v_mbcnt_lo_u32_b32 v2, -1, 0
	v_mbcnt_hi_u32_b32 v2, -1, v2
	s_cbranch_vccnz .Lw3_wait
	s_load_dwordx2 s[0:1], s[2:3], 0x60
	v_add_u32_e32 v3, s53, v2
	v_ashrrev_i32_e32 v5, 3, v3
	v_ashrrev_i32_e32 v3, 6, v3
	s_movk_i32 s6, 0x90
	v_and_b32_e32 v4, 63, v2
	v_and_b32_e32 v2, 7, v2
	v_lshlrev_b32_e32 v6, 3, v3
	v_lshlrev_b32_e32 v8, 4, v3
	v_mul_lo_u32 v3, v5, s6
	s_waitcnt lgkmcnt(0)
	s_add_u32 s4, s10, 0x2800000
	v_mad_u32_u24 v7, v4, s6, 0
	v_add_u32_e32 v9, 0, v3
	v_lshlrev_b32_e32 v10, 4, v2
	v_lshlrev_b32_e32 v2, 3, v2
	s_addc_u32 s5, s11, 0
	v_mov_b32_e32 v3, 0
	s_lshl_b32 s12, s66, 6
	s_lshl_b32 s13, s54, 6
	v_add_u32_e32 v7, v7, v8
	v_add_u32_e32 v8, v9, v10
	v_lshlrev_b32_e32 v2, 1, v2
	s_mov_b32 s14, s66

;     __device__ void init(int b_, int G_, int c_) { so.init(TB, 42 * 256, G_, c_); G = G_; c = c_; b = b_; gstart = b_ == 0 ? 0 : 256 + 192 * b_; ng = b_ == 0 ? 448 : 192; }
; __device__ __forceinline__ KParams kparams() { unsigned long long a = (unsigned long long)__builtin_amdgcn_kernarg_segment_ptr(); asm volatile("" : "+s"(a)); return (KParams)a; }
; __global__ void __launch_bounds__(512, 2) mega(Params p_unused) {
;     ...
;     {
;         KParams kp = kparams(); unsigned char* ws = kp->ws;
;         pg8::StaticOrder S; S.init(MT, DFF, (int)gridDim.x, (int)blockIdx.x);
;         pg8::Gemm gm{WSP(bf16_t, WS_X1B), WSP(bf16_t, WS_WUP), MT, DFF, DM, DM, DM}; EpiUp E{WSP(float, WS_SS2), WSP(bf16_t, WS_H)};
;         pg8::gemm_phase<EpiUp, pg8::StaticOrder>(wv, lds, gm, S, E);
.Lgwt3_done:
	s_barrier
	s_mov_b64 s[0:1], s[56:57]
	s_cmpk_lt_u32 s53, 0x100
	s_cbranch_scc1 .Lgprio_up
	s_setprio 1
